# IN_DA trailing context-key conversion batched (4 items, 8 loads in flight) in both DA layers
# baseline (speedup 1.0000x reference)
.LBB0_668:
	s_andn2_saveexec_b64 s[6:7], s[6:7]
	s_cbranch_execz .LBB0_665
	v_cmp_le_i32_e32 vcc, s9, v20
	s_cbranch_vccnz .LBB0_665
	v_and_or_b32 v128, v27, s16, v23
	v_ashrrev_i32_e32 v129, 19, v27
	v_lshrrev_b32_e32 v128, 10, v128
	v_lshl_or_b32 v126, v129, 10, v128
	v_ashrrev_i32_e32 v127, 31, v126
	v_lshlrev_b64 v[126:127], 12, v[126:127]
	v_lshl_add_u64 v[126:127], v[4:5], 0, v[126:127]
	global_load_dwordx4 v[118:121], v[126:127], off
	global_load_dwordx4 v[122:125], v[126:127], off offset:16
	v_mad_i32_i24 v129, v129, s8, v41
	v_or_b32_e32 v126, v129, v128
	v_ashrrev_i32_e32 v127, 31, v129
	v_lshlrev_b64 v[126:127], 11, v[126:127]
	v_lshl_add_u64 v[126:127], v[2:3], 0, v[126:127]
	s_mul_i32 s98, s13, 1
	v_add_u32_e32 v141, s98, v27
	v_and_or_b32 v140, v141, s16, v23
	v_ashrrev_i32_e32 v141, 19, v141
	v_lshrrev_b32_e32 v140, 10, v140
	v_lshl_or_b32 v138, v141, 10, v140
	v_ashrrev_i32_e32 v139, 31, v138
	v_lshlrev_b64 v[138:139], 12, v[138:139]
	v_lshl_add_u64 v[138:139], v[4:5], 0, v[138:139]
	global_load_dwordx4 v[130:133], v[138:139], off
	global_load_dwordx4 v[134:137], v[138:139], off offset:16
	v_mad_i32_i24 v141, v141, s8, v41
	v_or_b32_e32 v138, v141, v140
	v_ashrrev_i32_e32 v139, 31, v141
	v_lshlrev_b64 v[138:139], 11, v[138:139]
	v_lshl_add_u64 v[138:139], v[2:3], 0, v[138:139]
	s_mul_i32 s98, s13, 2
	v_add_u32_e32 v153, s98, v27
	v_and_or_b32 v152, v153, s16, v23
	v_ashrrev_i32_e32 v153, 19, v153
	v_lshrrev_b32_e32 v152, 10, v152
	v_lshl_or_b32 v150, v153, 10, v152
	v_ashrrev_i32_e32 v151, 31, v150
	v_lshlrev_b64 v[150:151], 12, v[150:151]
	v_lshl_add_u64 v[150:151], v[4:5], 0, v[150:151]
	global_load_dwordx4 v[142:145], v[150:151], off
	global_load_dwordx4 v[146:149], v[150:151], off offset:16
	v_mad_i32_i24 v153, v153, s8, v41
	v_or_b32_e32 v150, v153, v152
	v_ashrrev_i32_e32 v151, 31, v153
	v_lshlrev_b64 v[150:151], 11, v[150:151]
	v_lshl_add_u64 v[150:151], v[2:3], 0, v[150:151]
	s_mul_i32 s98, s13, 3
	v_add_u32_e32 v165, s98, v27
	v_and_or_b32 v164, v165, s16, v23
	v_ashrrev_i32_e32 v165, 19, v165
	v_lshrrev_b32_e32 v164, 10, v164
	v_lshl_or_b32 v162, v165, 10, v164
	v_ashrrev_i32_e32 v163, 31, v162
	v_lshlrev_b64 v[162:163], 12, v[162:163]
	v_lshl_add_u64 v[162:163], v[4:5], 0, v[162:163]
	global_load_dwordx4 v[154:157], v[162:163], off
	global_load_dwordx4 v[158:161], v[162:163], off offset:16
	v_mad_i32_i24 v165, v165, s8, v41
	v_or_b32_e32 v162, v165, v164
	v_ashrrev_i32_e32 v163, 31, v165
	v_lshlrev_b64 v[162:163], 11, v[162:163]
	v_lshl_add_u64 v[162:163], v[2:3], 0, v[162:163]
	s_waitcnt vmcnt(7)
	v_cvt_pk_bf16_f32 v118, v118, v119
	v_cvt_pk_bf16_f32 v119, v120, v121
	s_waitcnt vmcnt(6)
	v_cvt_pk_bf16_f32 v120, v122, v123
	v_cvt_pk_bf16_f32 v121, v124, v125
	global_store_dwordx4 v[126:127], v[118:121], off
	s_waitcnt vmcnt(6)
	v_cvt_pk_bf16_f32 v130, v130, v131
	v_cvt_pk_bf16_f32 v131, v132, v133
	s_waitcnt vmcnt(5)
	v_cvt_pk_bf16_f32 v132, v134, v135
	v_cvt_pk_bf16_f32 v133, v136, v137
	global_store_dwordx4 v[138:139], v[130:133], off
	s_waitcnt vmcnt(5)
	v_cvt_pk_bf16_f32 v142, v142, v143
	v_cvt_pk_bf16_f32 v143, v144, v145
	s_waitcnt vmcnt(4)
	v_cvt_pk_bf16_f32 v144, v146, v147
	v_cvt_pk_bf16_f32 v145, v148, v149
	global_store_dwordx4 v[150:151], v[142:145], off
	s_waitcnt vmcnt(4)
	v_cvt_pk_bf16_f32 v154, v154, v155
	v_cvt_pk_bf16_f32 v155, v156, v157
	s_waitcnt vmcnt(3)
	v_cvt_pk_bf16_f32 v156, v158, v159
	v_cvt_pk_bf16_f32 v157, v160, v161
	global_store_dwordx4 v[162:163], v[154:157], off
	s_branch .LBB0_665

.LBB0_2207:
	s_andn2_saveexec_b64 s[6:7], s[6:7]
	s_cbranch_execz .LBB0_2204
	v_cmp_le_i32_e32 vcc, s9, v20
	s_cbranch_vccnz .LBB0_2204
	v_and_or_b32 v128, v27, s17, v23
	v_ashrrev_i32_e32 v129, 19, v27
	v_lshrrev_b32_e32 v128, 10, v128
	v_lshlrev_b32_e32 v126, 10, v129
	v_or3_b32 v126, v128, v126, s15
	v_ashrrev_i32_e32 v127, 31, v126
	v_lshlrev_b64 v[126:127], 12, v[126:127]
	v_lshl_add_u64 v[126:127], v[4:5], 0, v[126:127]
	global_load_dwordx4 v[118:121], v[126:127], off
	global_load_dwordx4 v[122:125], v[126:127], off offset:16
	v_mad_i32_i24 v129, v129, s8, v41
	v_or_b32_e32 v126, v129, v128
	v_ashrrev_i32_e32 v127, 31, v129
	v_lshlrev_b64 v[126:127], 11, v[126:127]
	v_lshl_add_u64 v[126:127], v[2:3], 0, v[126:127]
	s_mul_i32 s98, s13, 1
	v_add_u32_e32 v141, s98, v27
	v_and_or_b32 v140, v141, s17, v23
	v_ashrrev_i32_e32 v141, 19, v141
	v_lshrrev_b32_e32 v140, 10, v140
	v_lshlrev_b32_e32 v138, 10, v141
	v_or3_b32 v138, v140, v138, s15
	v_ashrrev_i32_e32 v139, 31, v138
	v_lshlrev_b64 v[138:139], 12, v[138:139]
	v_lshl_add_u64 v[138:139], v[4:5], 0, v[138:139]
	global_load_dwordx4 v[130:133], v[138:139], off
	global_load_dwordx4 v[134:137], v[138:139], off offset:16
	v_mad_i32_i24 v141, v141, s8, v41
	v_or_b32_e32 v138, v141, v140
	v_ashrrev_i32_e32 v139, 31, v141
	v_lshlrev_b64 v[138:139], 11, v[138:139]
	v_lshl_add_u64 v[138:139], v[2:3], 0, v[138:139]
	s_mul_i32 s98, s13, 2
	v_add_u32_e32 v153, s98, v27
	v_and_or_b32 v152, v153, s17, v23
	v_ashrrev_i32_e32 v153, 19, v153
	v_lshrrev_b32_e32 v152, 10, v152
	v_lshlrev_b32_e32 v150, 10, v153
	v_or3_b32 v150, v152, v150, s15
	v_ashrrev_i32_e32 v151, 31, v150
	v_lshlrev_b64 v[150:151], 12, v[150:151]
	v_lshl_add_u64 v[150:151], v[4:5], 0, v[150:151]
	global_load_dwordx4 v[142:145], v[150:151], off
	global_load_dwordx4 v[146:149], v[150:151], off offset:16
	v_mad_i32_i24 v153, v153, s8, v41
	v_or_b32_e32 v150, v153, v152
	v_ashrrev_i32_e32 v151, 31, v153
	v_lshlrev_b64 v[150:151], 11, v[150:151]
	v_lshl_add_u64 v[150:151], v[2:3], 0, v[150:151]
	s_mul_i32 s98, s13, 3
	v_add_u32_e32 v165, s98, v27
	v_and_or_b32 v164, v165, s17, v23
	v_ashrrev_i32_e32 v165, 19, v165
	v_lshrrev_b32_e32 v164, 10, v164
	v_lshlrev_b32_e32 v162, 10, v165
	v_or3_b32 v162, v164, v162, s15
	v_ashrrev_i32_e32 v163, 31, v162
	v_lshlrev_b64 v[162:163], 12, v[162:163]
	v_lshl_add_u64 v[162:163], v[4:5], 0, v[162:163]
	global_load_dwordx4 v[154:157], v[162:163], off
	global_load_dwordx4 v[158:161], v[162:163], off offset:16
	v_mad_i32_i24 v165, v165, s8, v41
	v_or_b32_e32 v162, v165, v164
	v_ashrrev_i32_e32 v163, 31, v165
	v_lshlrev_b64 v[162:163], 11, v[162:163]
	v_lshl_add_u64 v[162:163], v[2:3], 0, v[162:163]
	s_waitcnt vmcnt(7)
	v_cvt_pk_bf16_f32 v118, v118, v119
	v_cvt_pk_bf16_f32 v119, v120, v121
	s_waitcnt vmcnt(6)
	v_cvt_pk_bf16_f32 v120, v122, v123
	v_cvt_pk_bf16_f32 v121, v124, v125
	global_store_dwordx4 v[126:127], v[118:121], off
	s_waitcnt vmcnt(6)
	v_cvt_pk_bf16_f32 v130, v130, v131
	v_cvt_pk_bf16_f32 v131, v132, v133
	s_waitcnt vmcnt(5)
	v_cvt_pk_bf16_f32 v132, v134, v135
	v_cvt_pk_bf16_f32 v133, v136, v137
	global_store_dwordx4 v[138:139], v[130:133], off
	s_waitcnt vmcnt(5)
	v_cvt_pk_bf16_f32 v142, v142, v143
	v_cvt_pk_bf16_f32 v143, v144, v145
	s_waitcnt vmcnt(4)
	v_cvt_pk_bf16_f32 v144, v146, v147
	v_cvt_pk_bf16_f32 v145, v148, v149
	global_store_dwordx4 v[150:151], v[142:145], off
	s_waitcnt vmcnt(4)
	v_cvt_pk_bf16_f32 v154, v154, v155
	v_cvt_pk_bf16_f32 v155, v156, v157
	s_waitcnt vmcnt(3)
	v_cvt_pk_bf16_f32 v156, v158, v159
	v_cvt_pk_bf16_f32 v157, v160, v161
	global_store_dwordx4 v[162:163], v[154:157], off
	s_branch .LBB0_2204
